# attention: next-tile K/V global loads (address calc + 5 loads) hoisted to the head of each QK MFMA stream, on top of the row-sum and row-max shadow interleaves
# speedup vs baseline: 1.0120x; 1.0081x over previous
; __device__ __forceinline__ void finishSM(f32x16& p0, f32x16& p1, float alpha, float& l_reg, bf16x8& pa0, bf16x8& pa1, bf16x8& pa2, bf16x8& pa3) {
; #pragma unroll
;     for (int r = 0; r < 16; ++r) p1[r] = __builtin_amdgcn_exp2f(p1[r]);
;     float ps = 0;
; #pragma unroll
;     for (int r = 0; r < 16; ++r) ps += p0[r];
; #pragma unroll
;     for (int r = 0; r < 16; ++r) ps += p1[r];
;     { auto rr = __builtin_amdgcn_permlane32_swap(__float_as_uint(ps), __float_as_uint(ps), false, false);
;       ps = __uint_as_float(rr[0]) + __uint_as_float(rr[1]); }
;     l_reg = l_reg * alpha + ps;
;     ...
;     PK4(p0, 0, pa0); PK4(p0, 8, pa1); PK4(p1, 0, pa2); PK4(p1, 8, pa3);
;     ...
; }
; template <int KB>
; __device__ __forceinline__ void qkt(f32x16& p0, f32x16& p1, const char* K_lds, int r32, int hi, const bf16x8* qr, const char* qbase) {
;     p0 = f32x16{}; p1 = f32x16{};
;     const char* kbp = K_lds + KB * SHM_K + r32 * KROW + hi * 16;
; #pragma unroll
;     for (int d0 = 0; d0 < 12; ++d0) { const char* a = kbp + d0 * 32;
;         bf16x8 b0 = *reinterpret_cast<const bf16x8*>(a);
;         bf16x8 b1 = *reinterpret_cast<const bf16x8*>(a + 32 * KROW);
;         const bf16x8 qf = d0 < 4 ? qr[d0 & 3] : *reinterpret_cast<const bf16x8*>(qbase + (d0 - 4) * 32);
;         p0 = __builtin_amdgcn_mfma_f32_32x32x16_bf16(b0, qf, p0, 0, 0, 0);
;         p1 = __builtin_amdgcn_mfma_f32_32x32x16_bf16(b1, qf, p1, 0, 0, 0); }
; }
.LBB0_1481:
	ds_read_b128 v[64:67], v202 offset:58368
	s_waitcnt vmcnt(0)
	ds_read_b128 v[100:103], v202 offset:58400
	v_add_u32_e32 v254, s31, v183
	v_add_u32_e32 v250, 0x80, v254
	v_min_u32_e32 v252, 0x100f, v250
	v_add_u32_e32 v251, 0x4080, v254
	v_add_u32_e32 v252, s14, v252
	v_cmp_gt_i32_e32 vcc, 16, v250
	s_nop 1
	v_cndmask_b32_e32 v250, v252, v251, vcc
	v_ashrrev_i32_e32 v251, 31, v250
	v_mad_i64_i32 v[252:253], s[0:1], v250, s33, v[184:185]
	v_lshlrev_b64 v[250:251], 12, v[250:251]
	v_lshl_add_u64 v[250:251], v[186:187], 0, v[250:251]
	global_load_dwordx4 v[146:149], v[250:251], off offset:128
	global_load_dwordx4 v[150:153], v[252:253], off
	global_load_dwordx4 v[154:157], v[252:253], off offset:128
	global_load_dwordx4 v[162:165], v[250:251], off
	global_load_dwordx4 v[158:161], v[252:253], off offset:256
	v_exp_f32_e32 v112, v172
	v_exp_f32_e32 v113, v173
	v_exp_f32_e32 v114, v170
	s_waitcnt lgkmcnt(1)
	v_mfma_f32_32x32x16_bf16 v[84:99], v[64:67], v[142:145], 0
	ds_read_b128 v[64:67], v206 offset:12800
	ds_read_b128 v[104:107], v206 offset:12832
	v_exp_f32_e32 v115, v171
	v_exp_f32_e32 v116, v168
	v_exp_f32_e32 v117, v169
	v_exp_f32_e32 v118, v166
	v_exp_f32_e32 v119, v167
	s_waitcnt lgkmcnt(1)
	v_mfma_f32_32x32x16_bf16 v[68:83], v[64:67], v[142:145], 0
	v_mfma_f32_32x32x16_bf16 v[84:99], v[100:103], v[138:141], v[84:99]
	ds_read_b128 v[64:67], v202 offset:58432
	ds_read_b128 v[100:103], v206 offset:12864
	v_add_f32_e32 v255, 0, v233
	v_add_f32_e32 v255, v235, v255
	s_waitcnt lgkmcnt(2)
	v_mfma_f32_32x32x16_bf16 v[68:83], v[104:107], v[138:141], v[68:83]
	v_add_f32_e32 v255, v231, v255
	v_add_f32_e32 v255, v234, v255
	s_waitcnt lgkmcnt(1)
	v_mfma_f32_32x32x16_bf16 v[84:99], v[64:67], v[134:137], v[84:99]
	v_add_f32_e32 v255, v223, v255
	v_add_f32_e32 v255, v232, v255
	s_waitcnt lgkmcnt(0)
	v_mfma_f32_32x32x16_bf16 v[68:83], v[100:103], v[134:137], v[68:83]
	ds_read_b128 v[64:67], v202 offset:58464
	ds_read_b128 v[100:103], v206 offset:12896
	v_add_f32_e32 v255, v221, v255
	v_add_f32_e32 v255, v222, v255
	s_waitcnt lgkmcnt(1)
	v_mfma_f32_32x32x16_bf16 v[84:99], v[64:67], v[130:133], v[84:99]
	v_add_f32_e32 v255, v217, v255
	v_add_f32_e32 v255, v220, v255
	s_waitcnt lgkmcnt(0)
	v_mfma_f32_32x32x16_bf16 v[68:83], v[100:103], v[130:133], v[68:83]
	ds_read_b128 v[64:67], v202 offset:58496
	ds_read_b128 v[100:103], v206 offset:12928
	ds_read_b128 v[104:107], v201
	ds_read_b128 v[108:111], v201 offset:32
	v_add_f32_e32 v255, v215, v255
	v_add_f32_e32 v255, v218, v255
	s_waitcnt lgkmcnt(1)
	v_mfma_f32_32x32x16_bf16 v[84:99], v[64:67], v[104:107], v[84:99]
	v_mfma_f32_32x32x16_bf16 v[68:83], v[100:103], v[104:107], v[68:83]
	ds_read_b128 v[64:67], v202 offset:58528
	ds_read_b128 v[100:103], v206 offset:12960
	v_add_f32_e32 v255, v213, v255
	v_add_f32_e32 v255, v219, v255
	s_waitcnt lgkmcnt(1)
	v_mfma_f32_32x32x16_bf16 v[84:99], v[64:67], v[108:111], v[84:99]
	v_add_f32_e32 v255, v214, v255
	v_add_f32_e32 v255, v216, v255
	s_waitcnt lgkmcnt(0)
	v_mfma_f32_32x32x16_bf16 v[68:83], v[100:103], v[108:111], v[68:83]
	ds_read_b128 v[64:67], v202 offset:58560
	ds_read_b128 v[100:103], v206 offset:12992
	ds_read_b128 v[104:107], v201 offset:64
	v_exp_f32_e32 v108, v176
	v_exp_f32_e32 v109, v177
	v_exp_f32_e32 v110, v174
	v_exp_f32_e32 v111, v175
	v_add_f32_e32 v255, v112, v255
	v_add_f32_e32 v255, v113, v255
	s_waitcnt lgkmcnt(0)
	v_mfma_f32_32x32x16_bf16 v[84:99], v[64:67], v[104:107], v[84:99]
	v_mfma_f32_32x32x16_bf16 v[68:83], v[100:103], v[104:107], v[68:83]
	ds_read_b128 v[64:67], v202 offset:58592
	ds_read_b128 v[100:103], v206 offset:13024
	ds_read_b128 v[104:107], v201 offset:96
	v_add_f32_e32 v255, v114, v255
	v_add_f32_e32 v255, v115, v255
	s_waitcnt lgkmcnt(0)
	v_mfma_f32_32x32x16_bf16 v[84:99], v[64:67], v[104:107], v[84:99]
	v_mfma_f32_32x32x16_bf16 v[68:83], v[100:103], v[104:107], v[68:83]
	ds_read_b128 v[64:67], v202 offset:58624
	ds_read_b128 v[100:103], v206 offset:13056
	ds_read_b128 v[104:107], v201 offset:128
	v_add_f32_e32 v255, v116, v255
	v_add_f32_e32 v255, v117, v255
	s_waitcnt lgkmcnt(0)
	v_mfma_f32_32x32x16_bf16 v[84:99], v[64:67], v[104:107], v[84:99]
	v_mfma_f32_32x32x16_bf16 v[68:83], v[100:103], v[104:107], v[68:83]
	ds_read_b128 v[64:67], v202 offset:58656
	ds_read_b128 v[100:103], v206 offset:13088
	ds_read_b128 v[104:107], v201 offset:160
	v_add_f32_e32 v255, v118, v255
	v_add_f32_e32 v255, v119, v255
	s_waitcnt lgkmcnt(0)
	v_mfma_f32_32x32x16_bf16 v[84:99], v[64:67], v[104:107], v[84:99]
	v_mfma_f32_32x32x16_bf16 v[68:83], v[100:103], v[104:107], v[68:83]
	ds_read_b128 v[64:67], v202 offset:58688
	ds_read_b128 v[100:103], v206 offset:13120
	ds_read_b128 v[104:107], v201 offset:192
	v_add_f32_e32 v255, v108, v255
	v_add_f32_e32 v255, v109, v255
	s_waitcnt lgkmcnt(0)
	v_mfma_f32_32x32x16_bf16 v[84:99], v[64:67], v[104:107], v[84:99]
	v_mfma_f32_32x32x16_bf16 v[68:83], v[100:103], v[104:107], v[68:83]
	ds_read_b128 v[64:67], v202 offset:58720
	ds_read_b128 v[100:103], v206 offset:13152
	ds_read_b128 v[104:107], v201 offset:224
	v_add_f32_e32 v255, v110, v255
	v_add_f32_e32 v255, v111, v255
	s_waitcnt lgkmcnt(0)
	v_mfma_f32_32x32x16_bf16 v[84:99], v[64:67], v[104:107], v[84:99]
	v_mfma_f32_32x32x16_bf16 v[68:83], v[100:103], v[104:107], v[68:83]
	v_exp_f32_e32 v104, v180
	v_exp_f32_e32 v105, v181
	v_exp_f32_e32 v106, v178
	v_exp_f32_e32 v107, v179
	v_add_f32_e32 v255, v104, v255
	v_add_f32_e32 v255, v105, v255
	v_add_f32_e32 v255, v106, v255
	v_add_f32_e32 v210, v107, v255
	v_mov_b32_e32 v211, v210
	s_nop 1
	v_permlane32_swap_b32_e32 v210, v211
	v_cvt_pk_bf16_f32 v64, v233, v235
	v_cvt_pk_bf16_f32 v65, v231, v234
	v_cvt_pk_bf16_f32 v66, v223, v232
	v_cvt_pk_bf16_f32 v67, v221, v222
	v_cvt_pk_bf16_f32 v100, v217, v220
	v_cvt_pk_bf16_f32 v101, v215, v218
	v_cvt_pk_bf16_f32 v102, v213, v219
	v_cvt_pk_bf16_f32 v103, v214, v216
	v_cvt_pk_bf16_f32 v104, v104, v105
	v_cvt_pk_bf16_f32 v105, v106, v107
	v_cvt_pk_bf16_f32 v106, v108, v109
	v_cvt_pk_bf16_f32 v107, v110, v111
	v_cvt_pk_bf16_f32 v108, v112, v113
	v_cvt_pk_bf16_f32 v109, v114, v115
	v_cvt_pk_bf16_f32 v110, v116, v117
	v_cvt_pk_bf16_f32 v111, v118, v119
	s_nop 0
	v_permlane32_swap_b32_e32 v64, v66
	v_permlane32_swap_b32_e32 v65, v67
	v_permlane32_swap_b32_e32 v100, v102
	v_permlane32_swap_b32_e32 v101, v103
	v_permlane32_swap_b32_e32 v104, v106
	v_permlane32_swap_b32_e32 v105, v107
	v_permlane32_swap_b32_e32 v108, v110
	v_permlane32_swap_b32_e32 v109, v111
	s_add_i32 s0, s31, 0x7f
	s_cmp_le_i32 s0, s30
	s_cbranch_scc1 .La_pvmax1
; __device__ __forceinline__ void mask_tile(f32x16& p0, f32x16& p1, int dq) {
;     const float NEG = -__builtin_inff();
; #pragma unroll
;     for (int r = 0; r < 16; ++r) {
;         const int c = (r & 3) + 8 * (r >> 2);
;         if (dq - c < 0) p0[r] = NEG;
;         if (dq - c - 32 < 0) p1[r] = NEG;
;     }
; }
; template <int VB>
; __device__ __forceinline__ void pv_tile(f32x16* o, int vb0, bf16x8 pa0, bf16x8 pa1, bf16x8 pa2, bf16x8 pa3) {
;     ...
;     PV_D0(0); PV_D0(1); PV_D0(2); PV_D0(3);
	ds_read_b64_tr_b16 v[112:113], v199 offset:0
	ds_read_b64_tr_b16 v[114:115], v199 offset:0x800
	ds_read_b64_tr_b16 v[116:117], v199 offset:0x1000
	ds_read_b64_tr_b16 v[118:119], v199 offset:0x1800
	ds_read_b64_tr_b16 v[120:121], v199 offset:0x2000
	ds_read_b64_tr_b16 v[122:123], v199 offset:0x2800
	ds_read_b64_tr_b16 v[124:125], v199 offset:0x3000
	ds_read_b64_tr_b16 v[126:127], v199 offset:0x3800
	s_waitcnt lgkmcnt(0)
	s_nop 0
	v_mfma_f32_32x32x16_bf16 v[48:63], v[64:67], v[112:115], v[48:63]
	ds_read_b64_tr_b16 v[112:113], v199 offset:0x200
	ds_read_b64_tr_b16 v[114:115], v199 offset:0xa00
	v_mfma_f32_32x32x16_bf16 v[48:63], v[100:103], v[116:119], v[48:63]
	ds_read_b64_tr_b16 v[116:117], v199 offset:0x1200
	ds_read_b64_tr_b16 v[118:119], v199 offset:0x1a00
	v_mfma_f32_32x32x16_bf16 v[48:63], v[104:107], v[120:123], v[48:63]
	ds_read_b64_tr_b16 v[120:121], v199 offset:0x2200
	ds_read_b64_tr_b16 v[122:123], v199 offset:0x2a00
	v_mfma_f32_32x32x16_bf16 v[48:63], v[108:111], v[124:127], v[48:63]
	ds_read_b64_tr_b16 v[124:125], v199 offset:0x3200
	ds_read_b64_tr_b16 v[126:127], v199 offset:0x3a00
	s_waitcnt lgkmcnt(0)
	v_mfma_f32_32x32x16_bf16 v[32:47], v[64:67], v[112:115], v[32:47]
	ds_read_b64_tr_b16 v[112:113], v199 offset:0x400
	ds_read_b64_tr_b16 v[114:115], v199 offset:0xc00
	v_mfma_f32_32x32x16_bf16 v[32:47], v[100:103], v[116:119], v[32:47]
	ds_read_b64_tr_b16 v[116:117], v199 offset:0x1400
	ds_read_b64_tr_b16 v[118:119], v199 offset:0x1c00
	v_mfma_f32_32x32x16_bf16 v[32:47], v[104:107], v[120:123], v[32:47]
	ds_read_b64_tr_b16 v[120:121], v199 offset:0x2400
	ds_read_b64_tr_b16 v[122:123], v199 offset:0x2c00
	v_mfma_f32_32x32x16_bf16 v[32:47], v[108:111], v[124:127], v[32:47]
	ds_read_b64_tr_b16 v[124:125], v199 offset:0x3400
	ds_read_b64_tr_b16 v[126:127], v199 offset:0x3c00
	s_waitcnt lgkmcnt(0)
	v_mfma_f32_32x32x16_bf16 v[16:31], v[64:67], v[112:115], v[16:31]
	ds_read_b64_tr_b16 v[112:113], v199 offset:0x600
	ds_read_b64_tr_b16 v[114:115], v199 offset:0xe00
	v_mfma_f32_32x32x16_bf16 v[16:31], v[100:103], v[116:119], v[16:31]
	ds_read_b64_tr_b16 v[116:117], v199 offset:0x1600
	ds_read_b64_tr_b16 v[118:119], v199 offset:0x1e00
	v_mfma_f32_32x32x16_bf16 v[16:31], v[104:107], v[120:123], v[16:31]
	ds_read_b64_tr_b16 v[120:121], v199 offset:0x2600
	ds_read_b64_tr_b16 v[122:123], v199 offset:0x2e00
	v_mfma_f32_32x32x16_bf16 v[16:31], v[108:111], v[124:127], v[16:31]
	ds_read_b64_tr_b16 v[124:125], v199 offset:0x3600
	ds_read_b64_tr_b16 v[126:127], v199 offset:0x3e00
	s_waitcnt lgkmcnt(0)
	v_mfma_f32_32x32x16_bf16 v[0:15], v[64:67], v[112:115], v[0:15]
	s_add_i32 s0, s31, 0x7f
	s_cmp_le_i32 s0, s30
	v_mfma_f32_32x32x16_bf16 v[0:15], v[100:103], v[116:119], v[0:15]
	v_mfma_f32_32x32x16_bf16 v[0:15], v[104:107], v[120:123], v[0:15]
	v_mfma_f32_32x32x16_bf16 v[0:15], v[108:111], v[124:127], v[0:15]
	s_cbranch_scc1 .LBB0_1483
	v_add_u32_e32 v64, 64, v209
	v_cmp_gt_i32_e64 s[96:97], 26, v64
	v_cmp_gt_i32_e32 vcc, 27, v64
	v_cmp_gt_i32_e64 s[94:95], 25, v64
	v_cmp_gt_i32_e64 s[92:93], 24, v64
	v_cndmask_b32_e32 v99, v99, v228, vcc
	s_and_b64 vcc, vcc, s[96:97]
	v_cndmask_b32_e32 v98, v98, v228, vcc
	s_and_b64 vcc, vcc, s[94:95]
	v_cmp_gt_i32_e64 s[90:91], 19, v64
	v_cndmask_b32_e32 v97, v97, v228, vcc
	s_and_b64 vcc, vcc, s[92:93]
	v_cmp_gt_i32_e64 s[88:89], 18, v64
	v_cndmask_b32_e32 v96, v96, v228, vcc
	s_and_b64 vcc, vcc, s[90:91]
	v_cmp_gt_i32_e64 s[86:87], 17, v64
	v_cndmask_b32_e32 v95, v95, v228, vcc
	s_and_b64 vcc, vcc, s[88:89]
	v_cmp_gt_i32_e64 s[84:85], 16, v64
	v_cndmask_b32_e32 v94, v94, v228, vcc
	s_and_b64 vcc, vcc, s[86:87]
	v_cmp_gt_i32_e64 s[82:83], 11, v64
	v_cndmask_b32_e32 v93, v93, v228, vcc
	s_and_b64 vcc, vcc, s[84:85]
	v_cmp_gt_i32_e64 s[80:81], 10, v64
	v_cndmask_b32_e32 v92, v92, v228, vcc
	s_and_b64 vcc, vcc, s[82:83]
	v_cmp_gt_i32_e64 s[78:79], 9, v64
	v_cndmask_b32_e32 v91, v91, v228, vcc
	s_and_b64 vcc, vcc, s[80:81]
	v_cmp_gt_i32_e64 s[76:77], 8, v64
	v_cndmask_b32_e32 v90, v90, v228, vcc
	s_and_b64 vcc, vcc, s[78:79]
	v_cmp_gt_i32_e64 s[74:75], 3, v64
	v_cndmask_b32_e32 v89, v89, v228, vcc
	s_and_b64 vcc, vcc, s[76:77]
	v_cmp_gt_i32_e64 s[72:73], 2, v64
	v_cndmask_b32_e32 v88, v88, v228, vcc
	s_and_b64 vcc, vcc, s[74:75]
	v_cmp_gt_i32_e64 s[70:71], 1, v64
	v_cndmask_b32_e32 v87, v87, v228, vcc
	s_and_b64 vcc, vcc, s[72:73]
	v_cmp_gt_i32_e64 s[4:5], 0, v64
	v_cndmask_b32_e32 v86, v86, v228, vcc
	s_and_b64 vcc, vcc, s[70:71]
	v_cndmask_b32_e32 v85, v85, v228, vcc
	s_and_b64 vcc, vcc, s[4:5]
	v_cmp_gt_i32_e64 s[68:69], 58, v64
	v_cndmask_b32_e32 v84, v84, v228, vcc
	v_cmp_gt_i32_e32 vcc, 59, v64
	v_cmp_gt_i32_e64 s[66:67], 57, v64
	v_cmp_gt_i32_e64 s[64:65], 56, v64
	v_cndmask_b32_e32 v83, v83, v228, vcc
	s_and_b64 vcc, vcc, s[68:69]
	v_cndmask_b32_e32 v82, v82, v228, vcc
	s_and_b64 vcc, vcc, s[66:67]
	v_cmp_gt_i32_e64 s[62:63], 51, v64
	v_cndmask_b32_e32 v81, v81, v228, vcc
	s_and_b64 vcc, vcc, s[64:65]
	v_cmp_gt_i32_e64 s[60:61], 50, v64
	v_cndmask_b32_e32 v80, v80, v228, vcc
	s_and_b64 vcc, vcc, s[62:63]
	v_cmp_gt_i32_e64 s[58:59], 49, v64
	v_cndmask_b32_e32 v79, v79, v228, vcc
	s_and_b64 vcc, vcc, s[60:61]
	v_cmp_gt_i32_e64 s[56:57], 48, v64
	v_cndmask_b32_e32 v78, v78, v228, vcc
	s_and_b64 vcc, vcc, s[58:59]
	v_cmp_gt_i32_e64 s[54:55], 43, v64
	v_cndmask_b32_e32 v77, v77, v228, vcc
	s_and_b64 vcc, vcc, s[56:57]
	v_cmp_gt_i32_e64 s[52:53], 42, v64
	v_cndmask_b32_e32 v76, v76, v228, vcc
	s_and_b64 vcc, vcc, s[54:55]
	v_cmp_gt_i32_e64 s[50:51], 41, v64
	v_cndmask_b32_e32 v75, v75, v228, vcc
	s_and_b64 vcc, vcc, s[52:53]
	v_cmp_gt_i32_e64 s[46:47], 40, v64
	v_cndmask_b32_e32 v74, v74, v228, vcc
	s_and_b64 vcc, vcc, s[50:51]
	v_cmp_gt_i32_e64 s[44:45], 35, v64
	v_cndmask_b32_e32 v73, v73, v228, vcc
	s_and_b64 vcc, vcc, s[46:47]
	v_cmp_gt_i32_e64 s[42:43], 34, v64
	v_cndmask_b32_e32 v72, v72, v228, vcc
	s_and_b64 vcc, vcc, s[44:45]
	v_cmp_gt_i32_e64 s[0:1], 33, v64
	v_cndmask_b32_e32 v71, v71, v228, vcc
	s_and_b64 vcc, vcc, s[42:43]
	v_cmp_gt_i32_e64 s[6:7], 32, v64
	v_cndmask_b32_e32 v70, v70, v228, vcc
	s_and_b64 vcc, vcc, s[0:1]
	v_cndmask_b32_e32 v69, v69, v228, vcc
	s_and_b64 vcc, vcc, s[6:7]
	s_mov_b32 s97, 0x41000000
	v_cndmask_b32_e32 v68, v68, v228, vcc

; __device__ __forceinline__ void partialSM(f32x16& p0, f32x16& p1, float& m_reg, float& mn, float& alpha) {
;     ...
;     const float mnL = -mn * C2;
; #pragma unroll
;     for (int r = 0; r < 16; ++r) p0[r] = fmaf(p0[r], C2, mnL);
; #pragma unroll
;     for (int r = 0; r < 16; ++r) p1[r] = fmaf(p1[r], C2, mnL);
; #pragma unroll
;     for (int r = 0; r < 16; ++r) p0[r] = __builtin_amdgcn_exp2f(p0[r]);
.LBB0_1487:
	v_cndmask_b32_e64 v208, v64, v208, s[42:43]
	v_mul_f32_e32 v166, 0xbdd53b94, v208
	v_fmamk_f32 v64, v84, 0x3dd53b94, v166
	v_fmamk_f32 v65, v85, 0x3dd53b94, v166
	v_fmamk_f32 v66, v86, 0x3dd53b94, v166
	v_fmamk_f32 v67, v87, 0x3dd53b94, v166
	v_fmamk_f32 v100, v88, 0x3dd53b94, v166
	v_fmamk_f32 v101, v89, 0x3dd53b94, v166
	v_fmamk_f32 v102, v90, 0x3dd53b94, v166
	v_fmamk_f32 v103, v91, 0x3dd53b94, v166
	v_fmamk_f32 v104, v92, 0x3dd53b94, v166
	v_fmamk_f32 v105, v93, 0x3dd53b94, v166
	v_fmamk_f32 v106, v94, 0x3dd53b94, v166
	v_fmamk_f32 v107, v95, 0x3dd53b94, v166
	v_fmamk_f32 v96, v96, 0x3dd53b94, v166
	v_fmamk_f32 v97, v97, 0x3dd53b94, v166
	v_fmamk_f32 v98, v98, 0x3dd53b94, v166
	v_fmamk_f32 v99, v99, 0x3dd53b94, v166
	v_fmamk_f32 v84, v68, 0x3dd53b94, v166
	v_fmamk_f32 v93, v69, 0x3dd53b94, v166
	v_fmamk_f32 v94, v70, 0x3dd53b94, v166
	v_fmamk_f32 v95, v71, 0x3dd53b94, v166
	v_fmamk_f32 v167, v72, 0x3dd53b94, v166
	v_fmamk_f32 v85, v73, 0x3dd53b94, v166
	v_fmamk_f32 v86, v74, 0x3dd53b94, v166
	v_fmamk_f32 v87, v75, 0x3dd53b94, v166
	v_fmamk_f32 v88, v76, 0x3dd53b94, v166
	v_fmamk_f32 v89, v77, 0x3dd53b94, v166
	v_fmamk_f32 v90, v78, 0x3dd53b94, v166
	v_fmamk_f32 v91, v79, 0x3dd53b94, v166
	v_exp_f32_e32 v64, v64
	v_exp_f32_e32 v65, v65
	v_exp_f32_e32 v66, v66
	v_exp_f32_e32 v67, v67
	v_exp_f32_e32 v68, v100
	v_exp_f32_e32 v69, v101
	v_exp_f32_e32 v70, v102
	v_exp_f32_e32 v71, v103
	v_exp_f32_e32 v72, v104
	v_exp_f32_e32 v73, v105
	v_exp_f32_e32 v74, v106
	v_exp_f32_e32 v75, v107
	v_exp_f32_e32 v76, v96
	v_exp_f32_e32 v77, v97
	v_exp_f32_e32 v78, v98
	v_exp_f32_e32 v79, v99
	v_fmamk_f32 v92, v80, 0x3dd53b94, v166
	v_fmamk_f32 v168, v81, 0x3dd53b94, v166
	v_fmamk_f32 v169, v82, 0x3dd53b94, v166
	v_fmac_f32_e32 v166, 0x3dd53b94, v83
	s_waitcnt lgkmcnt(0)
	s_barrier
	ds_read_b128 v[80:83], v202 offset:45568
	ds_read_b128 v[96:99], v202 offset:32768
	ds_read_b128 v[170:173], v202 offset:32800
	s_add_i32 s0, s26, 1
	s_cmp_lt_u32 s0, s35
	s_cselect_b64 s[28:29], -1, 0
	s_cmp_ge_u32 s0, s35
	s_cbranch_scc1 .La_s3skip2
	v_add_u32_e32 v146, 0xc0, v254
	v_min_u32_e32 v148, 0x100f, v146
	v_add_u32_e32 v147, 0x40c0, v254
	v_add_u32_e32 v148, s14, v148
	v_cmp_gt_i32_e32 vcc, 16, v146
	s_nop 1
	v_cndmask_b32_e32 v146, v148, v147, vcc
	v_ashrrev_i32_e32 v147, 31, v146
	v_mad_i64_i32 v[158:159], s[0:1], v146, s33, v[184:185]
	v_lshlrev_b64 v[146:147], 12, v[146:147]
	v_lshl_add_u64 v[160:161], v[186:187], 0, v[146:147]
	global_load_dwordx4 v[146:149], v[160:161], off offset:128
	global_load_dwordx4 v[150:153], v[158:159], off
	global_load_dwordx4 v[154:157], v[158:159], off offset:128
	global_load_dwordx4 v[162:165], v[160:161], off
	s_nop 0
	global_load_dwordx4 v[158:161], v[158:159], off offset:256
; __device__ __forceinline__ void finishSM(f32x16& p0, f32x16& p1, float alpha, float& l_reg, bf16x8& pa0, bf16x8& pa1, bf16x8& pa2, bf16x8& pa3) {
; #pragma unroll
;     for (int r = 0; r < 16; ++r) p1[r] = __builtin_amdgcn_exp2f(p1[r]);
;     float ps = 0;
; #pragma unroll
;     for (int r = 0; r < 16; ++r) ps += p0[r];
; #pragma unroll
;     for (int r = 0; r < 16; ++r) ps += p1[r];
;     { auto rr = __builtin_amdgcn_permlane32_swap(__float_as_uint(ps), __float_as_uint(ps), false, false);
;       ps = __uint_as_float(rr[0]) + __uint_as_float(rr[1]); }
;     l_reg = l_reg * alpha + ps;
;     ...
;     PK4(p0, 0, pa0); PK4(p0, 8, pa1); PK4(p1, 0, pa2); PK4(p1, 8, pa3);
;     ...
; }
; template <int KB>
; __device__ __forceinline__ void qkt(f32x16& p0, f32x16& p1, const char* K_lds, int r32, int hi, const bf16x8* qr, const char* qbase) {
;     p0 = f32x16{}; p1 = f32x16{};
;     const char* kbp = K_lds + KB * SHM_K + r32 * KROW + hi * 16;
; #pragma unroll
;     for (int d0 = 0; d0 < 12; ++d0) { const char* a = kbp + d0 * 32;
;         bf16x8 b0 = *reinterpret_cast<const bf16x8*>(a);
;         bf16x8 b1 = *reinterpret_cast<const bf16x8*>(a + 32 * KROW);
;         const bf16x8 qf = d0 < 4 ? qr[d0 & 3] : *reinterpret_cast<const bf16x8*>(qbase + (d0 - 4) * 32);
;         p0 = __builtin_amdgcn_mfma_f32_32x32x16_bf16(b0, qf, p0, 0, 0, 0);
;         p1 = __builtin_amdgcn_mfma_f32_32x32x16_bf16(b1, qf, p1, 0, 0, 0); }
; }
.La_s3skip2:
	v_exp_f32_e32 v85, v85
	v_exp_f32_e32 v86, v86
	v_exp_f32_e32 v87, v87
	s_waitcnt lgkmcnt(1)
	v_mfma_f32_32x32x16_bf16 v[112:127], v[96:99], v[142:145], 0
	v_exp_f32_e32 v88, v88
	v_exp_f32_e32 v89, v89
	v_exp_f32_e32 v90, v90
	v_exp_f32_e32 v91, v91
	v_exp_f32_e32 v92, v92
	v_mfma_f32_32x32x16_bf16 v[96:111], v[80:83], v[142:145], 0
	ds_read_b128 v[80:83], v202 offset:45600
	s_waitcnt lgkmcnt(1)
	v_mfma_f32_32x32x16_bf16 v[112:127], v[170:173], v[138:141], v[112:127]
	v_add_f32_e32 v255, 0, v64
	v_add_f32_e32 v255, v65, v255
	s_waitcnt lgkmcnt(0)
	v_mfma_f32_32x32x16_bf16 v[96:111], v[80:83], v[138:141], v[96:111]
	ds_read_b128 v[80:83], v202 offset:32832
	ds_read_b128 v[170:173], v202 offset:45632
	v_add_f32_e32 v255, v66, v255
	v_add_f32_e32 v255, v67, v255
	s_waitcnt lgkmcnt(1)
	v_mfma_f32_32x32x16_bf16 v[112:127], v[80:83], v[134:137], v[112:127]
	v_add_f32_e32 v255, v68, v255
	v_add_f32_e32 v255, v69, v255
	s_waitcnt lgkmcnt(0)
	v_mfma_f32_32x32x16_bf16 v[96:111], v[170:173], v[134:137], v[96:111]
	ds_read_b128 v[80:83], v202 offset:32864
	ds_read_b128 v[170:173], v202 offset:45664
	v_add_f32_e32 v255, v70, v255
	v_add_f32_e32 v255, v71, v255
	s_waitcnt lgkmcnt(1)
	v_mfma_f32_32x32x16_bf16 v[112:127], v[80:83], v[130:133], v[112:127]
	v_add_f32_e32 v255, v72, v255
	v_add_f32_e32 v255, v73, v255
	s_waitcnt lgkmcnt(0)
	v_mfma_f32_32x32x16_bf16 v[96:111], v[170:173], v[130:133], v[96:111]
	ds_read_b128 v[80:83], v202 offset:32896
	ds_read_b128 v[170:173], v202 offset:45696
	ds_read_b128 v[174:177], v201
	ds_read_b128 v[178:181], v201 offset:32
	v_add_f32_e32 v255, v74, v255
	v_add_f32_e32 v255, v75, v255
	s_waitcnt lgkmcnt(1)
	v_mfma_f32_32x32x16_bf16 v[112:127], v[80:83], v[174:177], v[112:127]
	v_mfma_f32_32x32x16_bf16 v[96:111], v[170:173], v[174:177], v[96:111]
	ds_read_b128 v[80:83], v202 offset:32928
	ds_read_b128 v[170:173], v202 offset:45728
	v_add_f32_e32 v255, v76, v255
	v_add_f32_e32 v255, v77, v255
	s_waitcnt lgkmcnt(1)
	v_mfma_f32_32x32x16_bf16 v[112:127], v[80:83], v[178:181], v[112:127]
	v_add_f32_e32 v255, v78, v255
	v_add_f32_e32 v255, v79, v255
	s_waitcnt lgkmcnt(0)
	v_mfma_f32_32x32x16_bf16 v[96:111], v[170:173], v[178:181], v[96:111]
	ds_read_b128 v[80:83], v202 offset:32960
	ds_read_b128 v[170:173], v202 offset:45760
	ds_read_b128 v[174:177], v201 offset:64
	v_add_f32_e32 v255, v85, v255
	v_add_f32_e32 v255, v86, v255
	s_waitcnt lgkmcnt(0)
	v_mfma_f32_32x32x16_bf16 v[112:127], v[80:83], v[174:177], v[112:127]
	v_mfma_f32_32x32x16_bf16 v[96:111], v[170:173], v[174:177], v[96:111]
	ds_read_b128 v[80:83], v202 offset:32992
	ds_read_b128 v[170:173], v202 offset:45792
	ds_read_b128 v[174:177], v201 offset:96
	v_add_f32_e32 v255, v87, v255
	v_add_f32_e32 v255, v88, v255
	s_waitcnt lgkmcnt(0)
	v_mfma_f32_32x32x16_bf16 v[112:127], v[80:83], v[174:177], v[112:127]
	v_mfma_f32_32x32x16_bf16 v[96:111], v[170:173], v[174:177], v[96:111]
	ds_read_b128 v[80:83], v202 offset:33024
	ds_read_b128 v[170:173], v202 offset:45824
	ds_read_b128 v[174:177], v201 offset:128
	v_add_f32_e32 v255, v89, v255
	v_add_f32_e32 v255, v90, v255
	s_waitcnt lgkmcnt(0)
	v_mfma_f32_32x32x16_bf16 v[112:127], v[80:83], v[174:177], v[112:127]
	v_mfma_f32_32x32x16_bf16 v[96:111], v[170:173], v[174:177], v[96:111]
	ds_read_b128 v[80:83], v202 offset:33056
	ds_read_b128 v[170:173], v202 offset:45856
	ds_read_b128 v[174:177], v201 offset:160
	v_add_f32_e32 v255, v91, v255
	v_add_f32_e32 v255, v92, v255
	s_waitcnt lgkmcnt(0)
	v_mfma_f32_32x32x16_bf16 v[112:127], v[80:83], v[174:177], v[112:127]
	v_mfma_f32_32x32x16_bf16 v[96:111], v[170:173], v[174:177], v[96:111]
	ds_read_b128 v[80:83], v202 offset:33088
	ds_read_b128 v[170:173], v202 offset:45888
	ds_read_b128 v[174:177], v201 offset:192
	s_waitcnt lgkmcnt(0)
	v_mfma_f32_32x32x16_bf16 v[112:127], v[80:83], v[174:177], v[112:127]
	v_mfma_f32_32x32x16_bf16 v[96:111], v[170:173], v[174:177], v[96:111]
	ds_read_b128 v[80:83], v202 offset:33120
	ds_read_b128 v[170:173], v202 offset:45920
	ds_read_b128 v[174:177], v201 offset:224
	s_waitcnt lgkmcnt(0)
	v_mfma_f32_32x32x16_bf16 v[112:127], v[80:83], v[174:177], v[112:127]
	v_mfma_f32_32x32x16_bf16 v[96:111], v[170:173], v[174:177], v[96:111]
	v_exp_f32_e32 v83, v95
	v_exp_f32_e32 v95, v166
	v_exp_f32_e32 v80, v84
	v_exp_f32_e32 v81, v93
	v_exp_f32_e32 v82, v94
	v_exp_f32_e32 v84, v167
	v_exp_f32_e32 v93, v168
	v_exp_f32_e32 v94, v169
	v_add_f32_e32 v255, v80, v255
	v_add_f32_e32 v255, v81, v255
	v_add_f32_e32 v255, v82, v255
	v_add_f32_e32 v255, v83, v255
	v_add_f32_e32 v255, v84, v255
	v_add_f32_e32 v255, v93, v255
	v_add_f32_e32 v255, v94, v255
	v_add_f32_e32 v236, v95, v255
	v_mov_b32_e32 v237, v236
	v_cvt_pk_bf16_f32 v166, v64, v65
	v_cvt_pk_bf16_f32 v167, v66, v67
	v_cvt_pk_bf16_f32 v168, v68, v69
	v_cvt_pk_bf16_f32 v169, v70, v71
	v_cvt_pk_bf16_f32 v170, v72, v73
	v_cvt_pk_bf16_f32 v171, v74, v75
	v_cvt_pk_bf16_f32 v172, v76, v77
	v_cvt_pk_bf16_f32 v173, v78, v79
	v_cvt_pk_bf16_f32 v174, v80, v81
	v_cvt_pk_bf16_f32 v175, v82, v83
	v_cvt_pk_bf16_f32 v176, v84, v85
	v_cvt_pk_bf16_f32 v177, v86, v87
	v_cvt_pk_bf16_f32 v178, v88, v89
	v_cvt_pk_bf16_f32 v179, v90, v91
	v_cvt_pk_bf16_f32 v180, v92, v93
	v_cvt_pk_bf16_f32 v181, v94, v95
	s_nop 1
	v_permlane32_swap_b32_e32 v236, v237
	v_permlane32_swap_b32_e32 v166, v168
	v_permlane32_swap_b32_e32 v167, v169
	v_permlane32_swap_b32_e32 v170, v172
	v_permlane32_swap_b32_e32 v171, v173
	v_permlane32_swap_b32_e32 v174, v176
	v_permlane32_swap_b32_e32 v175, v177
	v_permlane32_swap_b32_e32 v178, v180
	v_permlane32_swap_b32_e32 v179, v181
